# instruction selection: DPP row ops replace ds_bpermute round trips in the attention q prologue (16-lane sum + lane^4 exchange)
# baseline (speedup 1.0000x reference)
; __device__ __forceinline__ unsigned cvtpk(float lo, float hi) { f32x2_t v = {lo, hi}; bf16x2_t b = __builtin_convertvector(v, bf16x2_t); return __builtin_bit_cast(unsigned, b); }
; __device__ __forceinline__ float bf2f(short v) { return __uint_as_float(((unsigned)(unsigned short)v) << 16); }
; template <bool FAST> __device__ __forceinline__ void attn_dense_body(const bf16_t* __restrict__ Qb, const bf16_t* __restrict__ Kh, const bf16_t* __restrict__ Vh, ...
;     ...
;       const bf16x8 raw = ld8(Qb + (long)row * LDQ + chunk * 8);
;       float v[8]; float ss = 0.f;
; #pragma unroll
;       for (int e = 0; e < 8; ++e) { v[e] = bf2f(raw[e]); ss += v[e] * v[e]; }
;       ss += __shfl_xor(ss, 1); ss += __shfl_xor(ss, 2); ss += __shfl_xor(ss, 4); ss += __shfl_xor(ss, 8);
;       const float rstd = (FAST ? SCALE * 1.4426950408889634f : 1.0f) / sqrtf(ss * (1.0f / 128.0f) + 1e-6f);
;       const int t = t0 + row, pos = (chunk < 8) ? (t >> 6) : (t & 63);
;       float o8[8];
; #pragma unroll
;       for (int e = 0; e < 8; ++e) v[e] *= rstd * gq[e];
; #pragma unroll
;       for (int e = 0; e < 8; ++e) { const float pr = __shfl_xor(v[e], 4); const f32x2a cs = rtab[pos * 32 + i0 + e];
;         o8[e] = second ? (v[e] * cs.x + pr * cs.y) : (v[e] * cs.x - pr * cs.y); }
;       u32x4 w = {cvtpk(o8[0], o8[1]), cvtpk(o8[2], o8[3]), cvtpk(o8[4], o8[5]), cvtpk(o8[6], o8[7])};
;       *(u32x4*)(lds + KSWZ(row, chunk * 16)) = w; }
.LBB0_428:
	v_add_co_u32_e32 v28, vcc, 0xfff70000, v10
	v_add_u32_e32 v27, s6, v26
	s_nop 0
	v_addc_co_u32_e32 v29, vcc, -1, v11, vcc
	global_load_dwordx4 v[28:31], v[28:29], off
	v_ashrrev_i32_e32 v32, 6, v27
	v_cndmask_b32_e64 v32, v23, v32, s[42:43]
	v_lshl_or_b32 v32, v32, 5, v17
	v_ashrrev_i32_e32 v33, 31, v32
	v_lshl_add_u64 v[44:45], v[32:33], 3, s[38:39]
	global_load_dwordx4 v[32:35], v[44:45], off offset:48
	global_load_dwordx4 v[36:39], v[44:45], off offset:32
	global_load_dwordx4 v[40:43], v[44:45], off offset:16
	s_nop 0
	global_load_dwordx4 v[44:47], v[44:45], off
	v_add_u32_e32 v27, 32, v27
	v_ashrrev_i32_e32 v27, 6, v27
	v_cndmask_b32_e64 v27, v24, v27, s[42:43]
	s_add_i32 s6, s6, 64
	s_cmpk_eq_i32 s6, 0x100
	s_waitcnt vmcnt(4)
	v_and_b32_e32 v55, 0xffff0000, v29
	v_lshlrev_b32_e32 v54, 16, v29
	v_and_b32_e32 v29, 0xffff0000, v28
	v_lshlrev_b32_e32 v28, 16, v28
	v_pk_mul_f32 v[58:59], v[28:29], v[28:29]
	v_pk_mul_f32 v[56:57], v[54:55], v[54:55]
	v_add_f32_e32 v58, v58, v59
	v_and_b32_e32 v49, 0xffff0000, v31
	v_lshlrev_b32_e32 v48, 16, v31
	v_and_b32_e32 v31, 0xffff0000, v30
	v_lshlrev_b32_e32 v30, 16, v30
	v_add_f32_e32 v56, v56, v58
	v_pk_mul_f32 v[52:53], v[30:31], v[30:31]
	v_add_f32_e32 v56, v57, v56
	v_add_f32_e32 v52, v52, v56
	v_pk_mul_f32 v[50:51], v[48:49], v[48:49]
	v_add_f32_e32 v52, v53, v52
	v_add_f32_e32 v50, v50, v52
	v_add_f32_e32 v50, v51, v50
	s_nop 1
	v_add_f32_dpp v50, v50, v50 quad_perm:[1,0,3,2] row_mask:0xf bank_mask:0xf
	s_nop 1
	v_add_f32_dpp v50, v50, v50 quad_perm:[2,3,0,1] row_mask:0xf bank_mask:0xf
	s_nop 1
	v_add_f32_dpp v50, v50, v50 row_half_mirror row_mask:0xf bank_mask:0xf
	s_nop 1
	v_add_f32_dpp v50, v50, v50 row_mirror row_mask:0xf bank_mask:0xf
	v_fmamk_f32 v50, v50, 0x3c000000, v204
	v_cmp_gt_f32_e32 vcc, s73, v50
	v_mul_f32_e32 v51, 0x4f800000, v50
	s_nop 0
	v_cndmask_b32_e32 v50, v50, v51, vcc
	v_sqrt_f32_e32 v51, v50
	s_nop 0
	v_add_u32_e32 v52, -1, v51
	v_fma_f32 v53, -v52, v51, v50
	v_cmp_ge_f32_e64 s[44:45], 0, v53
	v_add_u32_e32 v53, 1, v51
	s_nop 0
	v_cndmask_b32_e64 v52, v51, v52, s[44:45]
	v_fma_f32 v51, -v53, v51, v50
	v_cmp_lt_f32_e64 s[44:45], 0, v51
	s_nop 1
	v_cndmask_b32_e64 v51, v52, v53, s[44:45]
	v_mul_f32_e32 v52, 0x37800000, v51
	v_cndmask_b32_e32 v51, v51, v52, vcc
	v_cmp_class_f32_e32 vcc, v50, v205
	s_nop 1
	v_cndmask_b32_e32 v50, v51, v50, vcc
	v_div_scale_f32 v51, s[8:9], v50, v50, s0
	v_rcp_f32_e32 v52, v51
	s_nop 0
	v_fma_f32 v53, -v51, v52, 1.0
	v_fmac_f32_e32 v52, v53, v52
	v_div_scale_f32 v53, vcc, s0, v50, s0
	v_mul_f32_e32 v56, v53, v52
	v_fma_f32 v57, -v51, v56, v53
	v_fmac_f32_e32 v56, v57, v52
	v_fma_f32 v51, -v51, v56, v53
	v_div_fmas_f32 v51, v51, v52, v56
	v_div_fixup_f32 v50, v51, v50, s0
	v_pk_mul_f32 v[52:53], v[6:7], v[50:51] op_sel_hi:[1,0]
	s_nop 0
	v_pk_mul_f32 v[28:29], v[52:53], v[28:29]
	v_pk_mul_f32 v[52:53], v[8:9], v[50:51] op_sel_hi:[1,0]
	s_nop 0
	v_pk_mul_f32 v[52:53], v[52:53], v[54:55]
	v_pk_mul_f32 v[54:55], v[2:3], v[50:51] op_sel_hi:[1,0]
	v_pk_mul_f32 v[50:51], v[4:5], v[50:51] op_sel_hi:[1,0]
	v_pk_mul_f32 v[30:31], v[54:55], v[30:31]
	v_pk_mul_f32 v[48:49], v[50:51], v[48:49]
	s_nop 1
	v_mov_b32_dpp v50, v28 row_half_mirror row_mask:0xf bank_mask:0xf
	v_mov_b32_dpp v51, v29 row_half_mirror row_mask:0xf bank_mask:0xf
	s_nop 0
	v_mov_b32_dpp v50, v50 quad_perm:[3,2,1,0] row_mask:0xf bank_mask:0xf
	v_mov_b32_dpp v51, v51 quad_perm:[3,2,1,0] row_mask:0xf bank_mask:0xf
	s_waitcnt vmcnt(0)
	v_mov_b32_e32 v55, v46
	v_mov_b32_e32 v46, v45
	v_mov_b32_e32 v54, v44
	s_waitcnt lgkmcnt(0)
	v_pk_mul_f32 v[44:45], v[46:47], v[50:51]
	s_nop 0
	v_cndmask_b32_e64 v45, v45, -v45, s[40:41]
	v_cndmask_b32_e64 v44, v44, -v44, s[40:41]
	v_pk_fma_f32 v[28:29], v[54:55], v[28:29], v[44:45]
	s_nop 1
	v_mov_b32_dpp v44, v52 row_half_mirror row_mask:0xf bank_mask:0xf
	v_mov_b32_dpp v45, v53 row_half_mirror row_mask:0xf bank_mask:0xf
	s_nop 0
	v_mov_b32_dpp v44, v44 quad_perm:[3,2,1,0] row_mask:0xf bank_mask:0xf
	v_mov_b32_dpp v45, v45 quad_perm:[3,2,1,0] row_mask:0xf bank_mask:0xf
	v_mov_b32_e32 v47, v42
	v_mov_b32_e32 v42, v41
	v_mov_b32_e32 v46, v40
	v_cvt_pk_bf16_f32 v28, v28, v29
	s_waitcnt lgkmcnt(0)
	v_pk_mul_f32 v[40:41], v[42:43], v[44:45]
	s_nop 1
	v_mov_b32_dpp v42, v30 row_half_mirror row_mask:0xf bank_mask:0xf
	v_mov_b32_dpp v43, v31 row_half_mirror row_mask:0xf bank_mask:0xf
	s_nop 0
	v_mov_b32_dpp v42, v42 quad_perm:[3,2,1,0] row_mask:0xf bank_mask:0xf
	v_mov_b32_dpp v43, v43 quad_perm:[3,2,1,0] row_mask:0xf bank_mask:0xf
	v_mov_b32_e32 v45, v38
	v_mov_b32_e32 v38, v37
	v_mov_b32_e32 v44, v36
	v_cndmask_b32_e64 v41, v41, -v41, s[40:41]
	s_waitcnt lgkmcnt(0)
	v_pk_mul_f32 v[36:37], v[38:39], v[42:43]
	v_mov_b32_e32 v39, v34
	v_cndmask_b32_e64 v37, v37, -v37, s[40:41]
	v_cndmask_b32_e64 v36, v36, -v36, s[40:41]
	v_pk_fma_f32 v[30:31], v[44:45], v[30:31], v[36:37]
	s_nop 1
	v_mov_b32_dpp v36, v48 row_half_mirror row_mask:0xf bank_mask:0xf
	v_mov_b32_dpp v37, v49 row_half_mirror row_mask:0xf bank_mask:0xf
	s_nop 0
	v_mov_b32_dpp v36, v36 quad_perm:[3,2,1,0] row_mask:0xf bank_mask:0xf
	v_mov_b32_dpp v37, v37 quad_perm:[3,2,1,0] row_mask:0xf bank_mask:0xf
	v_mov_b32_e32 v34, v33
	v_mov_b32_e32 v38, v32
	v_cndmask_b32_e64 v40, v40, -v40, s[40:41]
	v_pk_fma_f32 v[40:41], v[46:47], v[52:53], v[40:41]
	s_waitcnt lgkmcnt(0)
; __device__ __forceinline__ unsigned cvtpk(float lo, float hi) { f32x2_t v = {lo, hi}; bf16x2_t b = __builtin_convertvector(v, bf16x2_t); return __builtin_bit_cast(unsigned, b); }
; __device__ __forceinline__ float bf2f(short v) { return __uint_as_float(((unsigned)(unsigned short)v) << 16); }
; template <bool FAST> __device__ __forceinline__ void attn_dense_body(const bf16_t* __restrict__ Qb, const bf16_t* __restrict__ Kh, const bf16_t* __restrict__ Vh, ...
;     ...
;       const bf16x8 raw = ld8(Qb + (long)row * LDQ + chunk * 8);
;       float v[8]; float ss = 0.f;
; #pragma unroll
;       for (int e = 0; e < 8; ++e) { v[e] = bf2f(raw[e]); ss += v[e] * v[e]; }
;       ss += __shfl_xor(ss, 1); ss += __shfl_xor(ss, 2); ss += __shfl_xor(ss, 4); ss += __shfl_xor(ss, 8);
;       const float rstd = (FAST ? SCALE * 1.4426950408889634f : 1.0f) / sqrtf(ss * (1.0f / 128.0f) + 1e-6f);
;       const int t = t0 + row, pos = (chunk < 8) ? (t >> 6) : (t & 63);
;       float o8[8];
; #pragma unroll
;       for (int e = 0; e < 8; ++e) v[e] *= rstd * gq[e];
; #pragma unroll
;       for (int e = 0; e < 8; ++e) { const float pr = __shfl_xor(v[e], 4); const f32x2a cs = rtab[pos * 32 + i0 + e];
;         o8[e] = second ? (v[e] * cs.x + pr * cs.y) : (v[e] * cs.x - pr * cs.y); }
;       u32x4 w = {cvtpk(o8[0], o8[1]), cvtpk(o8[2], o8[3]), cvtpk(o8[4], o8[5]), cvtpk(o8[6], o8[7])};
;       *(u32x4*)(lds + KSWZ(row, chunk * 16)) = w; }
	v_pk_mul_f32 v[32:33], v[34:35], v[36:37]
	v_cvt_pk_bf16_f32 v29, v40, v41
	v_cndmask_b32_e64 v33, v33, -v33, s[40:41]
	v_cndmask_b32_e64 v32, v32, -v32, s[40:41]
	v_pk_fma_f32 v[32:33], v[38:39], v[48:49], v[32:33]
	v_cvt_pk_bf16_f32 v30, v30, v31
	v_cvt_pk_bf16_f32 v31, v32, v33
	ds_write_b128 v25, v[28:31]
	global_load_dwordx4 v[28:31], v[10:11], off
	v_lshl_or_b32 v32, v27, 5, v17
	v_ashrrev_i32_e32 v33, 31, v32
	v_lshl_add_u64 v[44:45], v[32:33], 3, s[38:39]
	global_load_dwordx4 v[32:35], v[44:45], off offset:48
	global_load_dwordx4 v[36:39], v[44:45], off offset:32
	global_load_dwordx4 v[40:43], v[44:45], off offset:16
	s_nop 0
	global_load_dwordx4 v[44:47], v[44:45], off
	v_lshl_add_u64 v[10:11], v[10:11], 0, s[4:5]
	s_waitcnt vmcnt(4)
	v_and_b32_e32 v55, 0xffff0000, v29
	v_lshlrev_b32_e32 v54, 16, v29
	v_and_b32_e32 v29, 0xffff0000, v28
	v_lshlrev_b32_e32 v28, 16, v28
	v_pk_mul_f32 v[58:59], v[28:29], v[28:29]
	v_pk_mul_f32 v[56:57], v[54:55], v[54:55]
	v_add_f32_e32 v27, v58, v59
	v_and_b32_e32 v49, 0xffff0000, v31
	v_lshlrev_b32_e32 v48, 16, v31
	v_and_b32_e32 v31, 0xffff0000, v30
	v_lshlrev_b32_e32 v30, 16, v30
	v_add_f32_e32 v27, v56, v27
	v_pk_mul_f32 v[52:53], v[30:31], v[30:31]
	v_add_f32_e32 v27, v57, v27
	v_add_f32_e32 v27, v52, v27
	v_pk_mul_f32 v[50:51], v[48:49], v[48:49]
	v_add_f32_e32 v27, v53, v27
	v_add_f32_e32 v27, v50, v27
	v_add_f32_e32 v27, v51, v27
	s_nop 1
	v_add_f32_dpp v27, v27, v27 quad_perm:[1,0,3,2] row_mask:0xf bank_mask:0xf
	s_nop 1
	v_add_f32_dpp v27, v27, v27 quad_perm:[2,3,0,1] row_mask:0xf bank_mask:0xf
	s_nop 1
	v_add_f32_dpp v27, v27, v27 row_half_mirror row_mask:0xf bank_mask:0xf
	s_nop 1
	v_add_f32_dpp v27, v27, v27 row_mirror row_mask:0xf bank_mask:0xf
	v_fmamk_f32 v27, v27, 0x3c000000, v204
	v_cmp_gt_f32_e32 vcc, s73, v27
	v_mul_f32_e32 v50, 0x4f800000, v27
	s_nop 0
	v_cndmask_b32_e32 v27, v27, v50, vcc
	v_sqrt_f32_e32 v50, v27
	s_nop 0
	v_add_u32_e32 v51, -1, v50
	v_fma_f32 v52, -v51, v50, v27
	v_cmp_ge_f32_e64 s[44:45], 0, v52
	v_add_u32_e32 v52, 1, v50
	s_nop 0
	v_cndmask_b32_e64 v51, v50, v51, s[44:45]
	v_fma_f32 v50, -v52, v50, v27
	v_cmp_lt_f32_e64 s[44:45], 0, v50
	s_nop 1
	v_cndmask_b32_e64 v50, v51, v52, s[44:45]
	v_mul_f32_e32 v51, 0x37800000, v50
	v_cndmask_b32_e32 v50, v50, v51, vcc
	v_cmp_class_f32_e32 vcc, v27, v205
	s_nop 1
	v_cndmask_b32_e32 v27, v50, v27, vcc
	v_div_scale_f32 v50, s[8:9], v27, v27, s0
	v_rcp_f32_e32 v51, v50
	s_nop 0
	v_fma_f32 v52, -v50, v51, 1.0
	v_fmac_f32_e32 v51, v52, v51
	v_div_scale_f32 v52, vcc, s0, v27, s0
	v_mul_f32_e32 v53, v52, v51
	v_fma_f32 v56, -v50, v53, v52
	v_fmac_f32_e32 v53, v56, v51
	v_fma_f32 v50, -v50, v53, v52
	v_div_fmas_f32 v50, v50, v51, v53
	v_div_fixup_f32 v50, v50, v27, s0
	v_pk_mul_f32 v[52:53], v[6:7], v[50:51] op_sel_hi:[1,0]
	s_nop 0
	v_pk_mul_f32 v[28:29], v[52:53], v[28:29]
	v_pk_mul_f32 v[52:53], v[8:9], v[50:51] op_sel_hi:[1,0]
	s_nop 0
	v_pk_mul_f32 v[52:53], v[52:53], v[54:55]
	v_pk_mul_f32 v[54:55], v[2:3], v[50:51] op_sel_hi:[1,0]
	v_pk_mul_f32 v[50:51], v[4:5], v[50:51] op_sel_hi:[1,0]
	v_pk_mul_f32 v[30:31], v[54:55], v[30:31]
	v_pk_mul_f32 v[48:49], v[50:51], v[48:49]
	s_nop 1
	v_mov_b32_dpp v50, v28 row_half_mirror row_mask:0xf bank_mask:0xf
	v_mov_b32_dpp v51, v29 row_half_mirror row_mask:0xf bank_mask:0xf
	s_nop 0
	v_mov_b32_dpp v50, v50 quad_perm:[3,2,1,0] row_mask:0xf bank_mask:0xf
	v_mov_b32_dpp v51, v51 quad_perm:[3,2,1,0] row_mask:0xf bank_mask:0xf
	s_waitcnt vmcnt(0)
	v_mov_b32_e32 v55, v46
	v_mov_b32_e32 v46, v45
	v_mov_b32_e32 v54, v44
	s_waitcnt lgkmcnt(0)
	v_pk_mul_f32 v[44:45], v[46:47], v[50:51]
	s_nop 0
	v_cndmask_b32_e64 v45, v45, -v45, s[40:41]
	v_cndmask_b32_e64 v44, v44, -v44, s[40:41]
	v_pk_fma_f32 v[28:29], v[54:55], v[28:29], v[44:45]
	s_nop 1
	v_mov_b32_dpp v44, v52 row_half_mirror row_mask:0xf bank_mask:0xf
	v_mov_b32_dpp v45, v53 row_half_mirror row_mask:0xf bank_mask:0xf
	s_nop 0
	v_mov_b32_dpp v44, v44 quad_perm:[3,2,1,0] row_mask:0xf bank_mask:0xf
	v_mov_b32_dpp v45, v45 quad_perm:[3,2,1,0] row_mask:0xf bank_mask:0xf
	v_mov_b32_e32 v47, v42
	v_mov_b32_e32 v42, v41
	v_mov_b32_e32 v46, v40
	v_cvt_pk_bf16_f32 v28, v28, v29
	s_waitcnt lgkmcnt(0)
	v_pk_mul_f32 v[40:41], v[42:43], v[44:45]
	s_nop 1
	v_mov_b32_dpp v42, v30 row_half_mirror row_mask:0xf bank_mask:0xf
	v_mov_b32_dpp v43, v31 row_half_mirror row_mask:0xf bank_mask:0xf
	s_nop 0
	v_mov_b32_dpp v42, v42 quad_perm:[3,2,1,0] row_mask:0xf bank_mask:0xf
	v_mov_b32_dpp v43, v43 quad_perm:[3,2,1,0] row_mask:0xf bank_mask:0xf
	v_mov_b32_e32 v45, v38
	v_mov_b32_e32 v38, v37
	v_mov_b32_e32 v44, v36
	v_cndmask_b32_e64 v41, v41, -v41, s[40:41]
	s_waitcnt lgkmcnt(0)
	v_pk_mul_f32 v[36:37], v[38:39], v[42:43]
	v_mov_b32_e32 v39, v34
	v_cndmask_b32_e64 v37, v37, -v37, s[40:41]
	v_cndmask_b32_e64 v36, v36, -v36, s[40:41]
	v_pk_fma_f32 v[30:31], v[44:45], v[30:31], v[36:37]
	s_nop 1
	v_mov_b32_dpp v36, v48 row_half_mirror row_mask:0xf bank_mask:0xf
	v_mov_b32_dpp v37, v49 row_half_mirror row_mask:0xf bank_mask:0xf
	s_nop 0
	v_mov_b32_dpp v36, v36 quad_perm:[3,2,1,0] row_mask:0xf bank_mask:0xf
	v_mov_b32_dpp v37, v37 quad_perm:[3,2,1,0] row_mask:0xf bank_mask:0xf
	v_mov_b32_e32 v34, v33
	v_mov_b32_e32 v38, v32
	v_cndmask_b32_e64 v40, v40, -v40, s[40:41]
	v_pk_fma_f32 v[40:41], v[46:47], v[52:53], v[40:41]
	s_waitcnt lgkmcnt(0)
	v_pk_mul_f32 v[32:33], v[34:35], v[36:37]
	v_cvt_pk_bf16_f32 v29, v40, v41
	v_cndmask_b32_e64 v33, v33, -v33, s[40:41]
	v_cndmask_b32_e64 v32, v32, -v32, s[40:41]
	v_pk_fma_f32 v[32:33], v[38:39], v[48:49], v[32:33]
	v_cvt_pk_bf16_f32 v30, v30, v31
	v_cvt_pk_bf16_f32 v31, v32, v33
	ds_write_b128 v25, v[28:31] offset:8192
	v_add_u32_e32 v25, 0x4000, v25
	s_cbranch_scc0 .LBB0_428
; __device__ __forceinline__ int v_st(int k, int c) { const int kk = (k & ~0xC) | ((k & 4) << 1) | ((k & 8) >> 1); return ((kk >> 3) * 4 + (c >> 5)) * 512 + ((kk & 7) * 32 + (c & 31)) * 2; }
; __device__ __forceinline__ int v_rd_base(int lane) { return ((lane & 3) << 3) | (((lane >> 2) & 3) << 6) | (((lane >> 4) & 1) << 5) | (((lane >> 5) & 1) << 8); }
; #define SLOAD(i, k0) do { const char* vb_ = (const char*)Vh + (size_t)(k0) * (LDV * 2); const char* kb_ = (const char*)Kh + (size_t)(k0) * (LDKK * 2); \
;     sr_[i].vs0 = *(const bf16x8*)(vb_ + voff); sr_[i].vs1 = *(const bf16x8*)(vb_ + 32 * LDV * 2 + voff); \
;     sr_[i].ks0 = *(const bf16x8*)(kb_ + koff); sr_[i].ks1 = *(const bf16x8*)(kb_ + 32 * LDKK * 2 + koff); } while (0)
; #define SWRITE(b, i) do { *(bf16x8*)((char*)V_lds + (b) * SHM_V + vst0) = sr_[i].vs0;          \
;     *(bf16x8*)((char*)V_lds + (b) * SHM_V + vst1) = sr_[i].vs1; int kc = sc * 2;               \
;     *(bf16x8*)((char*)K_lds + (b) * SHM_K + KSWZ(sr, kc)) = sr_[i].ks0;                       \
;     *(bf16x8*)((char*)K_lds + (b) * SHM_K + KSWZ(32 + sr, kc)) = sr_[i].ks1; } while (0)
; template <bool FAST> __device__ __forceinline__ void attn_dense_body(const bf16_t* __restrict__ Qb, const bf16_t* __restrict__ Kh, const bf16_t* __restrict__ Vh, ...
;     ...
;     __syncthreads();
; #pragma unroll
;     for (int d0 = 0; d0 < 8; ++d0) qr[d0] = *reinterpret_cast<const bf16x8*>(lds + KSWZ(wid * QBLK + r32, (d0 * 16 + hi * 8) * 2));
;     __syncthreads();
;   }
;   const int sr = tid >> 4, sc = (tid & 15) * 8, vst0 = v_st(sr, sc), vst1 = v_st(32 + sr, sc);
;   const int vb0 = (int)(uintptr_t)V_lds + v_rd_base(lane);
;   struct { bf16x8 vs0, vs1, ks0, ks1; } sr_[2];
;   const unsigned voff = (unsigned)(sr * LDV + sc) * 2u, koff = (unsigned)(sr * LDKK + sc) * 2u;
;     ...
;   f32x16 pA0, pA1, pB0, pB1; float mnA, mnB, alA, alB; bf16x8 pa0, pa1, pa2, pa3; constexpr int NT = SEQ / KVBLK;
;   constexpr int SE = 0, SO = 1;
;   SLOAD(SE, 0); asm volatile("s_waitcnt vmcnt(0)" ::: "memory"); SWRITE(0, SE); __syncthreads();
	s_lshl_b64 s[6:7], s[50:51], 23
	s_add_u32 s16, s12, s22
	s_addc_u32 s17, s13, s20
	s_add_u32 s8, s10, s6
	s_addc_u32 s9, s11, s7
	s_lshl_b32 s2, s2, 8
	s_add_u32 s8, s8, s2
	s_addc_u32 s9, s9, 0
	s_add_u32 s16, s16, s2
	s_addc_u32 s17, s17, 0
	s_ashr_i32 s2, s55, 6
	s_lshl_b32 s23, s2, 13
	v_lshlrev_b32_e32 v2, 8, v1
	v_and_b32_e32 v23, 0x1f00, v2
	v_lshrrev_b32_e32 v2, 1, v1
	v_lshlrev_b32_e32 v44, 4, v1
	s_add_i32 s23, s23, 0
	v_and_b32_e32 v3, 16, v2
	v_and_b32_e32 v4, 0x70, v44
	v_add_u32_e32 v5, s23, v23
	s_movk_i32 s23, 0x60
	v_bitop3_b32 v17, v2, v4, 16 bitop3:0x6c
	v_bitop3_b32 v34, v3, v4, s23 bitop3:0x36
	s_movk_i32 s23, 0x80
	v_add_u32_e32 v2, v5, v17
	v_bitop3_b32 v32, v3, v4, 32 bitop3:0x36
	v_bitop3_b32 v33, v3, v4, 64 bitop3:0x36
	v_bitop3_b32 v35, v3, v4, s23 bitop3:0x36
	s_movk_i32 s23, 0xa0
	s_waitcnt lgkmcnt(0)
	s_barrier
	v_add_u32_e32 v6, v5, v32
	ds_read_b128 v[144:147], v2
	ds_read_b128 v[140:143], v6
	v_add_u32_e32 v2, v5, v33
	v_bitop3_b32 v36, v3, v4, s23 bitop3:0x36
	s_movk_i32 s23, 0xc0
	v_add_u32_e32 v6, v5, v34
	ds_read_b128 v[136:139], v2
	ds_read_b128 v[132:135], v6
	v_add_u32_e32 v2, v5, v35
	v_bitop3_b32 v37, v3, v4, s23 bitop3:0x36
	s_movk_i32 s23, 0xe0
	v_add_u32_e32 v6, v5, v36
	ds_read_b128 v[128:131], v2
	ds_read_b128 v[124:127], v6
	v_add_u32_e32 v2, v5, v37
	v_bitop3_b32 v45, v3, v4, s23 bitop3:0x36
	v_add_u32_e32 v3, v5, v45
	ds_read_b128 v[120:123], v2
	ds_read_b128 v[116:119], v3
	v_mul_lo_u32 v2, v13, s1
	v_or_b32_e32 v18, v16, v2
	v_mov_b32_e32 v19, v114
	v_lshl_add_u64 v[48:49], s[16:17], 0, v[18:19]
	v_add_co_u32_e32 v2, vcc, s77, v48
	s_mov_b32 s16, 0x94000
	s_nop 0
	v_addc_co_u32_e32 v3, vcc, 0, v49, vcc
	v_add_co_u32_e32 v6, vcc, s16, v48
	v_lshl_or_b32 v20, v13, 10, v16
	s_nop 0
	v_addc_co_u32_e32 v7, vcc, 0, v49, vcc
	v_mov_b32_e32 v21, v114
	s_waitcnt lgkmcnt(0)
	s_barrier
	global_load_dwordx4 v[2:5], v[2:3], off offset:1024
	s_nop 0
	global_load_dwordx4 v[6:9], v[6:7], off offset:1024
	v_lshl_add_u64 v[50:51], s[8:9], 0, v[20:21]
	global_load_dwordx4 v[24:27], v20, s[8:9]
	s_mov_b32 s8, 0x8000
	v_add_co_u32_e32 v10, vcc, s8, v50
	v_lshrrev_b32_e32 v12, 2, v12
	s_nop 0
	v_addc_co_u32_e32 v11, vcc, 0, v51, vcc
	global_load_dwordx4 v[28:31], v[10:11], off
	v_and_b32_e32 v10, 0xfffff0, v13
	v_lshlrev_b32_e32 v11, 1, v13
	v_and_or_b32 v10, v11, 8, v10
	v_lshrrev_b32_e32 v11, 1, v13
	v_lshrrev_b32_e32 v10, 1, v10
	v_bfe_u32 v38, v1, 4, 2
	v_or_b32_e32 v10, v10, v12
	v_and_or_b32 v11, v11, 4, v38
	v_add_u32_e32 v13, 32, v13
	v_lshlrev_b32_e32 v10, 9, v10
	v_lshlrev_b32_e32 v11, 6, v11
	v_and_b32_e32 v16, 48, v16
	v_and_b32_e32 v38, 0xfffff0, v13
	v_lshlrev_b32_e32 v39, 1, v13
	v_or3_b32 v10, v10, v11, v16
	v_and_or_b32 v38, v39, 8, v38
	v_lshrrev_b32_e32 v38, 1, v38
	v_add_u32_e32 v217, 0, v10
	v_or_b32_e32 v12, v38, v12
	s_waitcnt vmcnt(0)
	v_lshlrev_b32_e32 v12, 9, v12
	v_or3_b32 v11, v12, v11, v16
	v_add_u32_e32 v218, 0, v11
	s_mov_b32 s8, 0x124000
	s_mov_b32 s16, 0x244000
	v_lshlrev_b32_e32 v1, 1, v1
	v_and_b32_e32 v1, 32, v1
	s_cmp_lg_u32 0, -1
	s_cselect_b32 s9, 0, 0
	s_lshl_b32 s3, s3, 1
	s_and_b32 s48, s3, 0x300
	s_waitcnt vmcnt(3)
	ds_write_b128 v217, v[2:5]
	v_or_b32_e32 v2, v14, v15
	v_add_u32_e32 v220, 0, v2
	v_lshl_or_b32 v2, v13, 8, v14
	v_add_u32_e32 v222, 0, v2
	v_or_b32_e32 v2, v17, v23
	v_add_u32_e32 v221, 0, v2
	s_waitcnt vmcnt(2)
	ds_write_b128 v218, v[6:9]
	s_waitcnt vmcnt(1)
	ds_write_b128 v220, v[24:27] offset:32768
	s_waitcnt vmcnt(0)
	ds_write_b128 v222, v[28:31] offset:32768
	s_waitcnt lgkmcnt(0)
	s_barrier
; #define SLOAD(i, k0) do { const char* vb_ = (const char*)Vh + (size_t)(k0) * (LDV * 2); const char* kb_ = (const char*)Kh + (size_t)(k0) * (LDKK * 2); \
;     sr_[i].vs0 = *(const bf16x8*)(vb_ + voff); sr_[i].vs1 = *(const bf16x8*)(vb_ + 32 * LDV * 2 + voff); \
;     sr_[i].ks0 = *(const bf16x8*)(kb_ + koff); sr_[i].ks1 = *(const bf16x8*)(kb_ + 32 * LDKK * 2 + koff); } while (0)
; #define SWRITE(b, i) do { *(bf16x8*)((char*)V_lds + (b) * SHM_V + vst0) = sr_[i].vs0;          \
;     *(bf16x8*)((char*)V_lds + (b) * SHM_V + vst1) = sr_[i].vs1; int kc = sc * 2;               \
;     *(bf16x8*)((char*)K_lds + (b) * SHM_K + KSWZ(sr, kc)) = sr_[i].ks0;                       \
;     *(bf16x8*)((char*)K_lds + (b) * SHM_K + KSWZ(32 + sr, kc)) = sr_[i].ks1; } while (0)
; #define SWAIT() asm volatile("s_waitcnt vmcnt(4)" ::: "memory")
; __device__ __forceinline__ void qkt(f32x16& p0, f32x16& p1, const bf16_t* Ks, const bf16x8* qr, int r32, int hi) {
;   p0 = f32x16{}; p1 = f32x16{};
;   for (int d0 = 0; d0 < 8; ++d0) { int cb = (d0 * 16 + hi * 8) * 2;
;     bf16x8 b0 = *reinterpret_cast<const bf16x8*>((const char*)Ks + KSWZ(r32, cb));
;     bf16x8 b1 = *reinterpret_cast<const bf16x8*>((const char*)Ks + KSWZ(32 + r32, cb));
;     p0 = __builtin_amdgcn_mfma_f32_32x32x16_bf16(b0, qr[d0], p0, 0, 0, 0);
;     p1 = __builtin_amdgcn_mfma_f32_32x32x16_bf16(b1, qr[d0], p1, 0, 0, 0); }
; template <bool FAST> __device__ __forceinline__ void attn_dense_body(const bf16_t* __restrict__ Qb, const bf16_t* __restrict__ Kh, const bf16_t* __restrict__ Vh, ...
;     ...
;   SLOAD(SE, 0); asm volatile("s_waitcnt vmcnt(0)" ::: "memory"); SWRITE(0, SE); __syncthreads();
;   qkt(pA0, pA1, K_lds, qr, r32, hi); psm<FAST>(pA0, pA1, m_reg, mnA, alA);
;   SLOAD(SO, KVBLK); SLOAD(SE, 2 * KVBLK);
;   SWAIT(); SWRITE(1, SO); __syncthreads();
	ds_read_b128 v[2:5], v221 offset:32768
	ds_read_b128 v[24:27], v221 offset:40960
	s_waitcnt lgkmcnt(1)
	v_mfma_f32_32x32x16_bf16 v[2:17], v[2:5], v[144:147], 0
	s_waitcnt lgkmcnt(0)
	v_mfma_f32_32x32x16_bf16 v[66:81], v[24:27], v[144:147], 0
	v_or_b32_e32 v24, v32, v23
	v_add_u32_e32 v223, 0, v24
	ds_read_b128 v[24:27], v223 offset:32768
	ds_read_b128 v[28:31], v223 offset:40960
	s_waitcnt lgkmcnt(1)
	v_mfma_f32_32x32x16_bf16 v[2:17], v[24:27], v[140:143], v[2:17]
	v_or_b32_e32 v24, v33, v23
	v_add_u32_e32 v219, 0, v24
	s_waitcnt lgkmcnt(0)
	v_mfma_f32_32x32x16_bf16 v[66:81], v[28:31], v[140:143], v[66:81]
	ds_read_b128 v[24:27], v219 offset:32768
	ds_read_b128 v[28:31], v219 offset:40960
	s_waitcnt lgkmcnt(1)
	v_mfma_f32_32x32x16_bf16 v[2:17], v[24:27], v[136:139], v[2:17]
	v_or_b32_e32 v24, v34, v23
	v_add_u32_e32 v216, 0, v24
	s_waitcnt lgkmcnt(0)
	v_mfma_f32_32x32x16_bf16 v[66:81], v[28:31], v[136:139], v[66:81]
	ds_read_b128 v[24:27], v216 offset:32768
	ds_read_b128 v[28:31], v216 offset:40960
	s_waitcnt lgkmcnt(1)
	v_mfma_f32_32x32x16_bf16 v[2:17], v[24:27], v[132:135], v[2:17]
	v_or_b32_e32 v24, v35, v23
	v_add_u32_e32 v215, 0, v24
	s_waitcnt lgkmcnt(0)
	v_mfma_f32_32x32x16_bf16 v[66:81], v[28:31], v[132:135], v[66:81]
	ds_read_b128 v[24:27], v215 offset:32768
	ds_read_b128 v[28:31], v215 offset:40960
	s_waitcnt lgkmcnt(1)
	v_mfma_f32_32x32x16_bf16 v[2:17], v[24:27], v[128:131], v[2:17]
	v_or_b32_e32 v24, v36, v23
	v_add_u32_e32 v214, 0, v24
	s_waitcnt lgkmcnt(0)
	v_mfma_f32_32x32x16_bf16 v[66:81], v[28:31], v[128:131], v[66:81]
	ds_read_b128 v[24:27], v214 offset:32768
	ds_read_b128 v[28:31], v214 offset:40960
	s_waitcnt lgkmcnt(1)
	v_mfma_f32_32x32x16_bf16 v[2:17], v[24:27], v[124:127], v[2:17]
	v_or_b32_e32 v24, v37, v23
	v_add_u32_e32 v213, 0, v24
	v_or_b32_e32 v23, v45, v23
	v_add_u32_e32 v224, 0, v23
	v_and_b32_e32 v23, 0xc0, v44
	v_and_or_b32 v23, v22, 24, v23
	v_and_b32_e32 v22, 0x100, v22
	s_waitcnt lgkmcnt(0)
	v_mfma_f32_32x32x16_bf16 v[66:81], v[28:31], v[124:127], v[66:81]
	ds_read_b128 v[24:27], v213 offset:32768
	ds_read_b128 v[28:31], v213 offset:40960
	v_or3_b32 v1, v23, v1, v22
	v_add_u32_e32 v180, s9, v1
	s_addk_i32 s9, 0x4000
	s_add_u32 s6, s46, s6
	s_addc_u32 s7, s47, s7
	v_lshl_add_u64 v[194:195], s[6:7], 0, v[20:21]
	s_waitcnt lgkmcnt(1)
	v_mfma_f32_32x32x16_bf16 v[2:17], v[24:27], v[120:123], v[2:17]
	v_add_co_u32_e32 v24, vcc, s8, v48
	s_mov_b32 s8, 0x1b4000
	s_nop 0
	v_addc_co_u32_e32 v25, vcc, 0, v49, vcc
	v_add_co_u32_e32 v32, vcc, s8, v48
	s_mov_b32 s8, 0x10000
	s_nop 0
	v_addc_co_u32_e32 v33, vcc, 0, v49, vcc
	v_add_co_u32_e32 v36, vcc, s8, v50
	s_mov_b32 s8, 0x18000
	s_nop 0
	v_addc_co_u32_e32 v37, vcc, 0, v51, vcc
	v_add_co_u32_e32 v40, vcc, s8, v50
	global_load_dwordx4 v[24:27], v[24:25], off offset:1024
	s_nop 0
	global_load_dwordx4 v[32:35], v[32:33], off offset:1024
	v_addc_co_u32_e32 v41, vcc, 0, v51, vcc
	global_load_dwordx4 v[36:39], v[36:37], off
	s_nop 0
	global_load_dwordx4 v[40:43], v[40:41], off
	s_waitcnt lgkmcnt(0)
	v_mfma_f32_32x32x16_bf16 v[66:81], v[28:31], v[120:123], v[66:81]
	ds_read_b128 v[28:31], v224 offset:32768
	ds_read_b128 v[44:47], v224 offset:40960
	s_add_u32 s6, s46, s22
	v_add_u32_e32 v115, s9, v1
	s_addc_u32 s7, s47, s20
	v_mov_b32_e32 v1, 0
	s_mov_b32 s8, 1
	s_waitcnt lgkmcnt(1)
	v_mfma_f32_32x32x16_bf16 v[2:17], v[28:31], v[116:119], v[2:17]
	v_lshl_add_u64 v[196:197], s[6:7], 0, v[18:19]
	v_mov_b32_e32 v18, 0
	v_mov_b32_e32 v19, v1
	v_mov_b32_e32 v20, v1
	v_mov_b32_e32 v21, v1
	v_mov_b32_e32 v22, v1
	v_mov_b32_e32 v23, v1
	s_nop 4
	v_exp_f32_e32 v229, v2
	v_add_co_u32_e32 v2, vcc, s16, v48
	v_exp_f32_e32 v230, v3
	s_nop 0
	v_addc_co_u32_e32 v3, vcc, 0, v49, vcc
	s_mov_b32 s16, 0x2d4000
	v_exp_f32_e32 v231, v4
	v_add_co_u32_e32 v4, vcc, s16, v48
	v_exp_f32_e32 v233, v5
	s_nop 0
	v_addc_co_u32_e32 v5, vcc, 0, v49, vcc
	s_mov_b32 s16, 0x20000
	global_load_dwordx4 v[148:151], v[2:3], off offset:1024
	global_load_dwordx4 v[152:155], v[4:5], off offset:1024
	v_add_co_u32_e32 v2, vcc, s16, v50
	s_mov_b32 s16, 0x28000
	s_nop 0
	v_addc_co_u32_e32 v3, vcc, 0, v51, vcc
	v_add_co_u32_e32 v4, vcc, s16, v50
	s_waitcnt lgkmcnt(0)
	v_mfma_f32_32x32x16_bf16 v[66:81], v[44:47], v[116:119], v[66:81]
	v_addc_co_u32_e32 v5, vcc, 0, v51, vcc
	global_load_dwordx4 v[156:159], v[2:3], off
	global_load_dwordx4 v[160:163], v[4:5], off
	v_exp_f32_e32 v234, v6
	v_exp_f32_e32 v236, v7
	v_exp_f32_e32 v232, v8
	v_exp_f32_e32 v235, v9
	v_exp_f32_e32 v199, v10
	v_exp_f32_e32 v200, v11
	v_exp_f32_e32 v201, v12
	v_exp_f32_e32 v227, v13
	v_exp_f32_e32 v198, v14
	v_exp_f32_e32 v225, v15
	v_exp_f32_e32 v226, v16
	v_exp_f32_e32 v228, v17
	s_waitcnt vmcnt(4)
	s_waitcnt vmcnt(7)
	ds_write_b128 v217, v[24:27] offset:16384
	s_waitcnt vmcnt(6)
	ds_write_b128 v218, v[32:35] offset:16384
	s_waitcnt vmcnt(5)
	ds_write_b128 v220, v[36:39] offset:49152
	s_waitcnt vmcnt(4)
	ds_write_b128 v222, v[40:43] offset:49152
	v_mov_b32_e32 v2, 0
	v_mov_b32_e32 v3, v1
	v_mov_b32_e32 v4, v1
	v_mov_b32_e32 v5, v1
	v_mov_b32_e32 v6, v1
	v_mov_b32_e32 v7, v1
	v_mov_b32_e32 v8, v1
	v_mov_b32_e32 v9, v1
	v_mov_b32_e32 v10, v1
	v_mov_b32_e32 v11, v1
	v_mov_b32_e32 v12, v1
	v_mov_b32_e32 v13, v1
	v_mov_b32_e32 v14, v1
	v_mov_b32_e32 v15, v1
	v_mov_b32_e32 v16, v1
	v_mov_b32_e32 v17, v1
	v_mov_b32_e32 v24, v1
	v_mov_b32_e32 v25, v1
	v_mov_b32_e32 v26, v1
	v_mov_b32_e32 v27, v1
	v_mov_b32_e32 v28, v1
	v_mov_b32_e32 v29, v1
	v_mov_b32_e32 v30, v1
	v_mov_b32_e32 v31, v1
	v_mov_b32_e32 v32, v1
	v_mov_b32_e32 v33, v1
	v_mov_b32_e32 v34, 0
	v_mov_b32_e32 v35, v1
	v_mov_b32_e32 v36, v1
	v_mov_b32_e32 v37, v1
	v_mov_b32_e32 v38, v1
	v_mov_b32_e32 v39, v1
	v_mov_b32_e32 v40, v1
	v_mov_b32_e32 v41, v1
	v_mov_b32_e32 v42, v1
	v_mov_b32_e32 v43, v1
	v_mov_b32_e32 v44, v1
	v_mov_b32_e32 v45, v1
	v_mov_b32_e32 v46, v1
	v_mov_b32_e32 v47, v1
	v_mov_b32_e32 v48, v1
	v_mov_b32_e32 v49, v1
	v_mov_b32_e32 v50, 0
	v_mov_b32_e32 v51, v1
	v_mov_b32_e32 v52, v1
	v_mov_b32_e32 v53, v1
	v_mov_b32_e32 v54, v1
	v_mov_b32_e32 v55, v1
	v_mov_b32_e32 v56, v1
	v_mov_b32_e32 v57, v1
	v_mov_b32_e32 v58, v1
	v_mov_b32_e32 v59, v1
	v_mov_b32_e32 v60, v1
	v_mov_b32_e32 v61, v1
	v_mov_b32_e32 v62, v1
	v_mov_b32_e32 v63, v1
	v_mov_b32_e32 v64, v1
	v_mov_b32_e32 v65, v1
	s_waitcnt lgkmcnt(0)
	s_barrier
	s_branch .LBB0_431
